# diff attention loop: packed row-sum, persistent QK init block, scalar live/near/far/mask tests; plus GEMM loop edits of v11
# baseline (speedup 1.0000x reference)
; #define AT_LOAD(TT) do { const u16* kn_ = Kp + (size_t)((TT) << 6) * ldk; const u16* vn_ = Vt + ((TT) << 6); \
;     _Pragma("unroll") for (int pi = 0; pi < 2; ++pi) vr[pi] = *(const u32x4*)(vn_ + (size_t)64 * pi * S + voff); \
;     _Pragma("unroll") for (int pi = 0; pi < NKC; ++pi) kr[pi] = *(const u32x4*)(kn_ + 64 * pi + koff); } while (0)
; template <int DQK, int KROW, bool BIAS, bool MAPS2>
; DI void attn_core(const int t, const u16* __restrict__ Q, int ldq, const u16* __restrict__ Kp, int ldk, const u16* __restrict__ Vt, int q0,
;                   char* lds, const float* lut, float b31, f32x16 (&o)[4], float& l_out) {
;     ...
;   const int lane = t & 63, w = t >> 6, r = lane & 31, hf = lane >> 5;
;   const int wr = MAPS2 ? (w & 3) : w, map = MAPS2 ? (w >> 2) : 0;
;   const int wq0 = q0 + 32 * wr, qrow = wq0 + r;
;   bf16x8 qf[NKS];
; #pragma unroll
;   for (int ks = 0; ks < NKS; ++ks) qf[ks] = *(const bf16x8*)(Q + (size_t)qrow * ldq + map * DQK + 16 * ks + 8 * hf);
; #pragma unroll
;   for (int dt = 0; dt < 4; ++dt)
; #pragma unroll
;     for (int i = 0; i < 16; ++i) o[dt][i] = 0.f;
;   float m_run = 0.f, l_run = 0.f;
;   const int ntile = (q0 >> 6) + (MAPS2 ? 2 : 4);
;   u32x4 kr[NKC], vr[2];
;   const unsigned koff = (unsigned)(t >> 3) * (unsigned)ldk + (unsigned)(t & 7) * 8u;
;   const unsigned voff = (unsigned)(t >> 3) * (unsigned)S + (unsigned)(t & 7) * 8u;
;   char* const klds = lds + (t >> 3) * KS + (t & 7) * 16;
;   char* const vlds = lds + AT_VOFF + (t >> 3) * VS + ((t & 7) >> 1) * 32 + (t & 1) * 8;
;     ...
;   AT_LOAD(0);
;   __syncthreads();
;   AT_WRITE(0);
;   AT_LOAD(1);
;   __syncthreads();
;   f32x16 s[2];
; #pragma nounroll
;   for (int kt = 0; kt < ntile; ++kt) {
; DI void diff_unit(const Params& p, const int t, int l, int h, int qb, char* lds) {
;     ...
;   __syncthreads();
;   if (t < 132) lut[t] = p.BLUT[h * 132 + (t > 128 ? 128 : t)];
;   const float b31 = p.BLUT[h * 132 + 128];
;   const int q0 = qb * 128, qrow = q0 + 32 * wr + r;
;   f32x16 o[4]; float lsum;
;   attn_core<64, 128, true, true>(t, p.QA + h * 128, 1024, p.KA + h * 128, 1024, p.VAT + (size_t)h * 128 * S, q0, lds, lut, b31, o, lsum);
.LBB0_231:
	s_or_b64 exec, exec, s[0:1]
	s_mul_i32 s0, s2, 3
	s_add_i32 s1, s0, s90
	v_readlane_b32 s64, v241, 1
	s_sub_i32 s0, 63, s1
	s_lshl_b64 s[88:89], s[4:5], 2
	v_readlane_b32 s68, v241, 5
	v_readlane_b32 s69, v241, 6
	s_add_u32 s88, s68, s88
	v_lshrrev_b32_e32 v0, 1, v233
	s_addc_u32 s89, s69, s89
	s_lshl_b32 s53, s0, 7
	v_and_b32_e32 v2, 0x60, v0
	s_waitcnt vmcnt(2)
	v_and_b32_e32 v150, 31, v233
	v_mov_b32_e32 v151, 0
	s_lshl_b32 s4, s62, 7
	v_or_b32_e32 v153, s53, v2
	global_load_dword v152, v151, s[88:89] offset:512
	s_lshl_b64 s[88:89], s[4:5], 1
	v_or_b32_e32 v144, v153, v150
	s_add_u32 s92, s42, s88
	v_ashrrev_i32_e32 v4, 8, v233
	v_ashrrev_i32_e32 v145, 31, v144
	s_addc_u32 s93, s43, s89
	v_lshlrev_b64 v[6:7], 11, v[144:145]
	v_lshlrev_b32_e32 v8, 6, v4
	v_bfe_u32 v3, v233, 5, 1
	v_lshl_add_u64 v[6:7], s[92:93], 0, v[6:7]
	v_ashrrev_i32_e32 v9, 31, v8
	v_lshl_add_u64 v[6:7], v[8:9], 1, v[6:7]
	v_lshlrev_b32_e32 v0, 4, v3
	s_add_u32 s94, s44, s88
	v_lshl_add_u64 v[6:7], v[6:7], 0, v[0:1]
	s_addc_u32 s95, s45, s89
	s_lshl_b64 s[96:97], s[4:5], 14
	global_load_dwordx4 v[112:115], v[6:7], off
	global_load_dwordx4 v[116:119], v[6:7], off offset:32
	global_load_dwordx4 v[120:123], v[6:7], off offset:64
	global_load_dwordx4 v[124:127], v[6:7], off offset:96
	v_and_b32_e32 v7, 7, v233
	s_add_u32 s96, s46, s96
	v_ashrrev_i32_e32 v5, 3, v233
	v_lshlrev_b32_e32 v14, 3, v7
	s_addc_u32 s97, s47, s97
	v_lshl_or_b32 v6, v5, 13, v14
	v_mul_lo_u32 v24, v5, s73
	v_lshlrev_b32_e32 v25, 4, v7
	v_mov_b32_e32 v7, v1
	v_lshl_or_b32 v14, v5, 10, v14
	v_lshlrev_b32_e32 v5, 7, v5
	v_and_b32_e32 v15, 0x60, v25
	v_lshl_add_u64 v[146:147], v[6:7], 1, s[96:97]
	v_sub_u32_e32 v5, v24, v5
	v_add_co_u32_e32 v22, vcc, s74, v146
	v_add_u32_e32 v5, v5, v15
	v_mov_b32_e32 v15, v1
	v_addc_co_u32_e32 v23, vcc, 0, v147, vcc
	v_lshl_add_u64 v[148:149], v[14:15], 1, s[94:95]
	global_load_dwordx4 v[6:9], v[146:147], off
	global_load_dwordx4 v[10:13], v[22:23], off
	global_load_dwordx4 v[14:17], v[148:149], off
	global_load_dwordx4 v[18:21], v[148:149], off offset:128
	v_lshlrev_b32_e32 v26, 3, v233
	s_waitcnt vmcnt(10)
	v_and_or_b32 v154, v26, 8, v5
	v_add_u32_e32 v145, v24, v25
	v_add_u32_e32 v5, 0xc800, v154
	s_waitcnt lgkmcnt(0)
	s_barrier
	s_mov_b64 s[92:93], 0x20000
	s_cmp_gt_u32 s1, 63
	v_readlane_b32 s65, v241, 2
	v_readlane_b32 s66, v241, 3
	v_readlane_b32 s67, v241, 4
	v_readlane_b32 s70, v241, 7
	v_readlane_b32 s71, v241, 8
	s_waitcnt vmcnt(1)
	ds_write_b128 v145, v[14:17]
	s_waitcnt vmcnt(0)
	ds_write_b128 v145, v[18:21] offset:128
	ds_write2_b64 v5, v[6:7], v[8:9] offset1:2
	v_add_u32_e32 v5, 0xe800, v154
	v_add_co_u32_e32 v8, vcc, 0x20000, v148
	ds_write2_b64 v5, v[10:11], v[12:13] offset0:128 offset1:130
	s_nop 0
	v_addc_co_u32_e32 v9, vcc, 0, v149, vcc
	global_load_dwordx4 v[128:131], v[146:147], off offset:128
	global_load_dwordx4 v[132:135], v[22:23], off offset:128
	v_lshl_add_u64 v[6:7], v[148:149], 0, s[92:93]
	global_load_dwordx4 v[136:139], v[8:9], off
	global_load_dwordx4 v[140:143], v[6:7], off offset:128
	s_waitcnt lgkmcnt(0)
	s_barrier
	s_cbranch_scc1 .LBB0_246
	s_lshl_b32 s4, s0, 1
	v_mad_u32_u24 v0, v150, s73, v0
	v_lshlrev_b32_e32 v157, 2, v3
	v_lshlrev_b32_e32 v3, 7, v150
	s_lshl_b32 s0, s90, 7
	v_lshl_add_u32 v156, v4, 7, v0
	v_sub_u32_e32 v158, v0, v3
	v_subrev_u32_e32 v0, s0, v2
	s_mul_i32 s0, s2, 0x180
	v_subrev_u32_e32 v0, s0, v0
	v_mov_b32_e32 v14, v1
	v_mov_b32_e32 v15, v1
	v_add_u32_e32 v159, 0x1f41, v0
	v_mov_b32_e32 v0, v1
	v_mov_b32_e32 v2, v1
	v_mov_b32_e32 v3, v1
	v_mov_b32_e32 v4, v1
	v_mov_b32_e32 v5, v1
	v_mov_b32_e32 v6, v1
	v_mov_b32_e32 v7, v1
	v_mov_b32_e32 v8, v1
	v_mov_b32_e32 v9, v1
	v_mov_b32_e32 v10, v1
	v_mov_b32_e32 v11, v1
	v_mov_b32_e32 v12, v1
	v_mov_b32_e32 v13, v1
	v_mov_b64_e32 v[78:79], v[14:15]
	v_mov_b64_e32 v[62:63], v[14:15]
	v_mov_b64_e32 v[46:47], v[14:15]
	v_mov_b64_e32 v[30:31], v[14:15]
	s_add_i32 s94, s4, 2
	v_or_b32_e32 v155, 31, v153
	v_sub_u32_e32 v160, v150, v157
	s_mov_b32 s90, 0
	v_mov_b32_e32 v161, 0
	v_mov_b64_e32 v[76:77], v[12:13]
	v_mov_b64_e32 v[74:75], v[10:11]
	v_mov_b64_e32 v[72:73], v[8:9]
	v_mov_b64_e32 v[70:71], v[6:7]
	v_mov_b64_e32 v[68:69], v[4:5]
	v_mov_b64_e32 v[66:67], v[2:3]
	v_mov_b64_e32 v[64:65], v[0:1]
	v_mov_b64_e32 v[60:61], v[12:13]
	v_mov_b64_e32 v[58:59], v[10:11]
	v_mov_b64_e32 v[56:57], v[8:9]
	v_mov_b64_e32 v[54:55], v[6:7]
	v_mov_b64_e32 v[52:53], v[4:5]
	v_mov_b64_e32 v[50:51], v[2:3]
	v_mov_b64_e32 v[48:49], v[0:1]
	v_mov_b64_e32 v[44:45], v[12:13]
	v_mov_b64_e32 v[42:43], v[10:11]
	v_mov_b64_e32 v[40:41], v[8:9]
	v_mov_b64_e32 v[38:39], v[6:7]
	v_mov_b64_e32 v[36:37], v[4:5]
	v_mov_b64_e32 v[34:35], v[2:3]
	v_mov_b64_e32 v[32:33], v[0:1]
	v_mov_b64_e32 v[28:29], v[12:13]
	v_mov_b64_e32 v[26:27], v[10:11]
	v_mov_b64_e32 v[24:25], v[8:9]
	v_mov_b64_e32 v[22:23], v[6:7]
	v_mov_b64_e32 v[20:21], v[4:5]
	v_mov_b64_e32 v[18:19], v[2:3]
	v_mov_b64_e32 v[16:17], v[0:1]
	v_mov_b32_e32 v151, 0
	v_mov_b32_e32 v184, 0
	v_mov_b32_e32 v185, 0
	v_readfirstlane_b32 s101, v155
	v_readfirstlane_b32 s100, v159
	v_mov_b32_e32 v188, v152
	v_mov_b32_e32 v189, v152
	v_mov_b32_e32 v190, v152
	v_mov_b32_e32 v191, v152
	v_mov_b32_e32 v192, v152
	v_mov_b32_e32 v193, v152
	v_mov_b32_e32 v194, v152
	v_mov_b32_e32 v195, v152
	v_mov_b32_e32 v196, v152
	v_mov_b32_e32 v197, v152
	v_mov_b32_e32 v198, v152
	v_mov_b32_e32 v199, v152
	v_mov_b32_e32 v200, v152
	v_mov_b32_e32 v201, v152
	v_mov_b32_e32 v202, v152
	v_mov_b32_e32 v203, v152
	s_mov_b32 s96, 0
	s_add_i32 s95, s96, 1
	s_cmp_ge_i32 s95, s94
	s_cbranch_scc1 .LBB0_235

; #define MFMA32(a, b, c) __builtin_amdgcn_mfma_f32_32x32x16_bf16((a), (b), (c), 0, 0, 0)
; template <int DQK, int KROW, bool BIAS, bool MAPS2>
; DI void attn_core(const int t, const u16* __restrict__ Q, int ldq, const u16* __restrict__ Kp, int ldk, const u16* __restrict__ Vt, int q0,
;                   char* lds, const float* lut, float b31, f32x16 (&o)[4], float& l_out) {
;     ...
;     const bool live = (kt << 6) <= wq0 + 31;
;     if (live) {
;       const int k0 = kt << 6;
;       const bool far = BIAS && (wq0 - (k0 + 63) >= 128);
;       const float init = (far ? b31 : 0.f) - m_run;
; #pragma unroll
;       for (int k2 = 0; k2 < 2; ++k2)
; #pragma unroll
;         for (int i = 0; i < 16; ++i) s[k2][i] = init;
;       {
;         constexpr int QBS = (NKS > 4) ? 2 : 4, NBT = NKS / QBS;
;         bf16x8 kfb[2][QBS][2];
;         const char* kbase = lds + (kt & 1) * AT_KBUF + r * KS + hf * 16 + map * (DQK * 2);
; #pragma unroll
;         for (int jq = 0; jq < QBS; ++jq)
; #pragma unroll
;           for (int k2 = 0; k2 < 2; ++k2) kfb[0][jq][k2] = *(const bf16x8*)(kbase + 32 * k2 * KS + jq * 32);
; #pragma unroll
;         for (int b = 0; b < NBT; ++b) {
;           if (b + 1 < NBT) {
; #pragma unroll
;             for (int jq = 0; jq < QBS; ++jq)
; #pragma unroll
;               for (int k2 = 0; k2 < 2; ++k2) kfb[(b + 1) & 1][jq][k2] = *(const bf16x8*)(kbase + 32 * k2 * KS + ((b + 1) * QBS + jq) * 32);
;           }
;           __builtin_amdgcn_sched_barrier(0);
;           __builtin_amdgcn_s_setprio(1);
; #pragma unroll
;           for (int jq = 0; jq < QBS; ++jq)
; #pragma unroll
;             for (int k2 = 0; k2 < 2; ++k2) s[k2] = MFMA32(kfb[b & 1][jq][k2], qf[b * QBS + jq], s[k2]);
;           __builtin_amdgcn_s_setprio(0);
;           __builtin_amdgcn_sched_barrier(0);
;         }
;       }
;       if (BIAS && !far) {
; #pragma unroll
;         for (int k2 = 0; k2 < 2; ++k2)
; #pragma unroll
;           for (int i = 0; i < 16; ++i) {
;             const int key = k0 + 32 * k2 + (i & 3) + 8 * (i >> 2) + 4 * hf;
;             int d = qrow - key; d = d < 0 ? 0 : (d > 128 ? 128 : d);
;             s[k2][i] += lut[d];
;           }
;       }
.LBB0_235:
	s_cmp_le_i32 s90, s101
	s_cbranch_scc0 .LBB0_243
	s_and_b32 s91, s96, 1
	s_mul_i32 s0, s91, 0x6400
	v_add_u32_e32 v0, s0, v156
	ds_read_b128 v[2:5], v0 offset:8704
	ds_read_b128 v[6:9], v0
	ds_read_b128 v[10:13], v0 offset:32
	ds_read_b128 v[162:165], v0 offset:8736
	ds_read_b128 v[166:169], v0 offset:64
	ds_read_b128 v[170:173], v0 offset:8768
	ds_read_b128 v[174:177], v0 offset:96
	ds_read_b128 v[178:181], v0 offset:8800
	s_cmpk_gt_i32 s100, 0x7f
	s_cbranch_scc0 .Ldt_near
	s_setprio 1
	s_waitcnt lgkmcnt(6)
	v_mfma_f32_32x32x16_bf16 v[96:111], v[6:9], v[112:115], v[188:203]
	v_mfma_f32_32x32x16_bf16 v[80:95], v[2:5], v[112:115], v[188:203]
	s_branch .Ldt_qk2
.Ldt_near:
	v_sub_f32_e32 v80, 0, v161
	s_setprio 1
	v_mov_b32_e32 v81, v80
	v_mov_b32_e32 v82, v80
	v_mov_b32_e32 v83, v80
	v_mov_b32_e32 v84, v80
	v_mov_b32_e32 v85, v80
	v_mov_b32_e32 v86, v80
	v_mov_b32_e32 v87, v80
	v_mov_b32_e32 v88, v80
	v_mov_b32_e32 v89, v80
	v_mov_b32_e32 v90, v80
	v_mov_b32_e32 v91, v80
	v_mov_b32_e32 v92, v80
	v_mov_b32_e32 v93, v80
	v_mov_b32_e32 v94, v80
	v_mov_b32_e32 v95, v80
	s_waitcnt lgkmcnt(6)
	s_nop 0
	v_mfma_f32_32x32x16_bf16 v[96:111], v[6:9], v[112:115], v[80:95]
	v_mfma_f32_32x32x16_bf16 v[80:95], v[2:5], v[112:115], v[80:95]
.Ldt_qk2:
	s_waitcnt lgkmcnt(5)
	v_mfma_f32_32x32x16_bf16 v[96:111], v[10:13], v[116:119], v[96:111]
	s_waitcnt lgkmcnt(4)
	v_mfma_f32_32x32x16_bf16 v[80:95], v[162:165], v[116:119], v[80:95]
	s_waitcnt lgkmcnt(3)
	v_mfma_f32_32x32x16_bf16 v[96:111], v[166:169], v[120:123], v[96:111]
	s_waitcnt lgkmcnt(2)
	v_mfma_f32_32x32x16_bf16 v[80:95], v[170:173], v[120:123], v[80:95]
	s_waitcnt lgkmcnt(1)
	v_mfma_f32_32x32x16_bf16 v[96:111], v[174:177], v[124:127], v[96:111]
	s_waitcnt lgkmcnt(0)
	v_mfma_f32_32x32x16_bf16 v[80:95], v[178:181], v[124:127], v[80:95]
	s_setprio 0
	s_cmpk_lt_i32 s100, 0x80
	s_cbranch_scc0 .LBB0_238
	v_add_u32_e32 v0, s100, v160
	v_add_u32_e32 v2, 63, v0
	v_add_u32_e32 v3, 62, v0
	v_add_u32_e32 v4, 61, v0
	v_add_u32_e32 v5, 60, v0
	v_add_u32_e32 v6, 55, v0
	v_add_u32_e32 v7, 54, v0
	v_add_u32_e32 v8, 53, v0
	v_add_u32_e32 v9, 52, v0
	v_add_u32_e32 v10, 47, v0
	v_add_u32_e32 v11, 46, v0
	v_add_u32_e32 v12, 45, v0
	v_add_u32_e32 v13, 44, v0
	v_add_u32_e32 v14, 39, v0
	v_add_u32_e32 v15, 38, v0
	v_add_u32_e32 v162, 37, v0
	v_add_u32_e32 v163, 36, v0
	v_add_u32_e32 v164, 31, v0
	v_add_u32_e32 v165, 30, v0
	v_add_u32_e32 v166, 29, v0
	v_add_u32_e32 v167, 28, v0
	v_add_u32_e32 v168, 23, v0
	v_add_u32_e32 v169, 22, v0
	v_add_u32_e32 v170, 21, v0
	v_add_u32_e32 v171, 20, v0
	v_add_u32_e32 v172, 15, v0
	v_add_u32_e32 v173, 14, v0
	v_add_u32_e32 v174, 13, v0
	v_add_u32_e32 v175, 12, v0
	v_add_u32_e32 v176, 7, v0
	v_add_u32_e32 v177, 6, v0
	v_add_u32_e32 v178, 5, v0
	v_med3_i32 v2, v2, 0, v229
	v_med3_i32 v3, v3, 0, v229
	v_med3_i32 v4, v4, 0, v229
	v_med3_i32 v5, v5, 0, v229
	v_med3_i32 v6, v6, 0, v229
	v_med3_i32 v7, v7, 0, v229
	v_med3_i32 v8, v8, 0, v229
	v_med3_i32 v9, v9, 0, v229
	v_med3_i32 v10, v10, 0, v229
	v_med3_i32 v11, v11, 0, v229
	v_med3_i32 v12, v12, 0, v229
	v_med3_i32 v13, v13, 0, v229
	v_med3_i32 v14, v14, 0, v229
	v_med3_i32 v15, v15, 0, v229
	v_med3_i32 v162, v162, 0, v229
	v_med3_i32 v163, v163, 0, v229
	v_med3_i32 v164, v164, 0, v229
	v_med3_i32 v165, v165, 0, v229
	v_med3_i32 v166, v166, 0, v229
	v_med3_i32 v167, v167, 0, v229
	v_med3_i32 v168, v168, 0, v229
	v_med3_i32 v169, v169, 0, v229
	v_med3_i32 v170, v170, 0, v229
	v_med3_i32 v171, v171, 0, v229
	v_med3_i32 v172, v172, 0, v229
	v_med3_i32 v173, v173, 0, v229
	v_med3_i32 v174, v174, 0, v229
	v_med3_i32 v175, v175, 0, v229
	v_med3_i32 v176, v176, 0, v229
	v_med3_i32 v177, v177, 0, v229
	v_med3_i32 v178, v178, 0, v229
	v_add_u32_e32 v0, 4, v0
	v_lshl_add_u32 v2, v2, 2, v228
	v_lshl_add_u32 v3, v3, 2, v228
	v_lshl_add_u32 v4, v4, 2, v228
	v_lshl_add_u32 v5, v5, 2, v228
	v_lshl_add_u32 v6, v6, 2, v228
	v_lshl_add_u32 v7, v7, 2, v228
	v_lshl_add_u32 v8, v8, 2, v228
	v_lshl_add_u32 v9, v9, 2, v228
	v_lshl_add_u32 v10, v10, 2, v228
	v_lshl_add_u32 v11, v11, 2, v228
	v_lshl_add_u32 v12, v12, 2, v228
	v_lshl_add_u32 v13, v13, 2, v228
	v_lshl_add_u32 v14, v14, 2, v228
	v_lshl_add_u32 v15, v15, 2, v228
	v_lshl_add_u32 v162, v162, 2, v228
	v_lshl_add_u32 v163, v163, 2, v228
	v_lshl_add_u32 v164, v164, 2, v228
	v_lshl_add_u32 v165, v165, 2, v228
	v_lshl_add_u32 v166, v166, 2, v228
	v_lshl_add_u32 v167, v167, 2, v228
	v_lshl_add_u32 v168, v168, 2, v228
	v_lshl_add_u32 v169, v169, 2, v228
	v_lshl_add_u32 v170, v170, 2, v228
	v_lshl_add_u32 v171, v171, 2, v228
	v_lshl_add_u32 v172, v172, 2, v228
	v_lshl_add_u32 v173, v173, 2, v228
	v_lshl_add_u32 v174, v174, 2, v228
	v_lshl_add_u32 v175, v175, 2, v228
	v_lshl_add_u32 v176, v176, 2, v228
	v_lshl_add_u32 v177, v177, 2, v228
	v_lshl_add_u32 v178, v178, 2, v228
	v_med3_i32 v0, v0, 0, v229
	ds_read_b32 v2, v2
	ds_read_b32 v3, v3
	ds_read_b32 v4, v4
	ds_read_b32 v5, v5
	ds_read_b32 v6, v6
	ds_read_b32 v7, v7
	ds_read_b32 v8, v8
	ds_read_b32 v9, v9
	ds_read_b32 v10, v10
	ds_read_b32 v11, v11
	ds_read_b32 v12, v12
	ds_read_b32 v13, v13
	ds_read_b32 v14, v14
	ds_read_b32 v15, v15
	ds_read_b32 v162, v162
	ds_read_b32 v163, v163
	ds_read_b32 v164, v164
	ds_read_b32 v165, v165
	ds_read_b32 v166, v166
	ds_read_b32 v167, v167
	ds_read_b32 v168, v168
	ds_read_b32 v169, v169
	ds_read_b32 v170, v170
	ds_read_b32 v171, v171
	v_lshl_add_u32 v0, v0, 2, v228
	ds_read_b32 v172, v172
	ds_read_b32 v173, v173
	ds_read_b32 v174, v174
	ds_read_b32 v175, v175
	ds_read_b32 v176, v176
	ds_read_b32 v177, v177
	ds_read_b32 v178, v178
	ds_read_b32 v179, v0
	s_waitcnt lgkmcnt(14)
	v_pk_add_f32 v[108:109], v[108:109], v[14:15]
	v_pk_add_f32 v[110:111], v[110:111], v[162:163]
	v_pk_add_f32 v[106:107], v[106:107], v[12:13]
	v_pk_add_f32 v[104:105], v[104:105], v[10:11]
	v_pk_add_f32 v[102:103], v[102:103], v[8:9]
	v_pk_add_f32 v[100:101], v[100:101], v[6:7]
	v_pk_add_f32 v[98:99], v[98:99], v[4:5]
	v_pk_add_f32 v[96:97], v[96:97], v[2:3]
	s_waitcnt lgkmcnt(0)
	v_pk_add_f32 v[94:95], v[94:95], v[178:179]
	v_pk_add_f32 v[92:93], v[92:93], v[176:177]
	v_pk_add_f32 v[90:91], v[90:91], v[174:175]
	v_pk_add_f32 v[88:89], v[88:89], v[172:173]
	v_pk_add_f32 v[86:87], v[86:87], v[170:171]
	v_pk_add_f32 v[84:85], v[84:85], v[168:169]
	v_pk_add_f32 v[82:83], v[82:83], v[166:167]
	v_pk_add_f32 v[80:81], v[80:81], v[164:165]
; template <int DQK, int KROW, bool BIAS, bool MAPS2>
; DI void attn_core(const int t, const u16* __restrict__ Q, int ldq, const u16* __restrict__ Kp, int ldk, const u16* __restrict__ Vt, int q0,
;                   char* lds, const float* lut, float b31, f32x16 (&o)[4], float& l_out) {
;     ...
;       if (k0 + 63 > wq0) {
; #pragma unroll
;         for (int k2 = 0; k2 < 2; ++k2)
; #pragma unroll
;           for (int i = 0; i < 16; ++i) {
;             const int key = k0 + 32 * k2 + (i & 3) + 8 * (i >> 2) + 4 * hf;
;             if (key > qrow) s[k2][i] = -INFINITY;
;           }
;       }
;       float mx = s[0][0];
; #pragma unroll
;       for (int k2 = 0; k2 < 2; ++k2)
; #pragma unroll
;         for (int i = 0; i < 16; ++i) mx = fmaxf(mx, s[k2][i]);
;       mx = xhalf_max(mx);
;       if (__builtin_amdgcn_ballot_w64(kt == 0 || mx > RESCALE_THR)) {
.LBB0_238:
	s_add_i32 s0, s90, 0x5e
	s_cmp_gt_i32 s0, s101
	s_cbranch_scc0 .LBB0_240
	v_add_u32_e32 v0, s90, v157
	v_cmp_le_i32_e32 vcc, v0, v144
	v_add_u32_e32 v2, 2, v0
	s_nop 0
	v_cndmask_b32_e32 v96, v230, v96, vcc
	v_cmp_lt_i32_e32 vcc, v0, v144
	s_nop 1
	v_cndmask_b32_e32 v97, v230, v97, vcc
	v_cmp_le_i32_e32 vcc, v2, v144
	v_add_u32_e32 v2, 3, v0
	s_nop 0
	v_cndmask_b32_e32 v98, v230, v98, vcc
	v_cmp_le_i32_e32 vcc, v2, v144
	v_add_u32_e32 v2, 8, v0
	s_nop 0
	v_cndmask_b32_e32 v99, v230, v99, vcc
	v_cmp_le_i32_e32 vcc, v2, v144
	v_add_u32_e32 v2, 9, v0
	s_nop 0
	v_cndmask_b32_e32 v100, v230, v100, vcc
	v_cmp_le_i32_e32 vcc, v2, v144
	v_add_u32_e32 v2, 10, v0
	s_nop 0
	v_cndmask_b32_e32 v101, v230, v101, vcc
	v_cmp_le_i32_e32 vcc, v2, v144
	v_add_u32_e32 v2, 11, v0
	s_nop 0
	v_cndmask_b32_e32 v102, v230, v102, vcc
	v_cmp_le_i32_e32 vcc, v2, v144
	v_add_u32_e32 v2, 16, v0
	s_nop 0
	v_cndmask_b32_e32 v103, v230, v103, vcc
	v_cmp_le_i32_e32 vcc, v2, v144
	v_add_u32_e32 v2, 17, v0
	s_nop 0
	v_cndmask_b32_e32 v104, v230, v104, vcc
	v_cmp_le_i32_e32 vcc, v2, v144
	v_add_u32_e32 v2, 18, v0
	s_nop 0
	v_cndmask_b32_e32 v105, v230, v105, vcc
	v_cmp_le_i32_e32 vcc, v2, v144
	v_add_u32_e32 v2, 19, v0
	s_nop 0
	v_cndmask_b32_e32 v106, v230, v106, vcc
	v_cmp_le_i32_e32 vcc, v2, v144
	v_add_u32_e32 v2, 24, v0
	s_nop 0
	v_cndmask_b32_e32 v107, v230, v107, vcc
	v_cmp_le_i32_e32 vcc, v2, v144
	v_add_u32_e32 v2, 25, v0
	s_nop 0
	v_cndmask_b32_e32 v108, v230, v108, vcc
	v_cmp_le_i32_e32 vcc, v2, v144
	v_add_u32_e32 v2, 26, v0
	s_nop 0
	v_cndmask_b32_e32 v109, v230, v109, vcc
	v_cmp_le_i32_e32 vcc, v2, v144
	v_add_u32_e32 v2, 27, v0
	s_nop 0
	v_cndmask_b32_e32 v110, v230, v110, vcc
	v_cmp_le_i32_e32 vcc, v2, v144
	v_add_u32_e32 v2, 32, v0
	s_nop 0
	v_cndmask_b32_e32 v111, v230, v111, vcc
	v_cmp_le_i32_e32 vcc, v2, v144
	v_add_u32_e32 v2, 33, v0
	s_nop 0
	v_cndmask_b32_e32 v80, v230, v80, vcc
	v_cmp_le_i32_e32 vcc, v2, v144
	v_add_u32_e32 v2, 34, v0
	s_nop 0
	v_cndmask_b32_e32 v81, v230, v81, vcc
	v_cmp_le_i32_e32 vcc, v2, v144
	v_add_u32_e32 v2, 35, v0
	s_nop 0
	v_cndmask_b32_e32 v82, v230, v82, vcc
	v_cmp_le_i32_e32 vcc, v2, v144
	v_add_u32_e32 v2, 40, v0
	s_nop 0
	v_cndmask_b32_e32 v83, v230, v83, vcc
	v_cmp_le_i32_e32 vcc, v2, v144
	v_add_u32_e32 v2, 41, v0
	s_nop 0
	v_cndmask_b32_e32 v84, v230, v84, vcc
	v_cmp_le_i32_e32 vcc, v2, v144
	v_add_u32_e32 v2, 42, v0
	s_nop 0
	v_cndmask_b32_e32 v85, v230, v85, vcc
	v_cmp_le_i32_e32 vcc, v2, v144
	v_add_u32_e32 v2, 43, v0
	s_nop 0
	v_cndmask_b32_e32 v86, v230, v86, vcc
	v_cmp_le_i32_e32 vcc, v2, v144
	v_add_u32_e32 v2, 48, v0
	s_nop 0
	v_cndmask_b32_e32 v87, v230, v87, vcc
	v_cmp_le_i32_e32 vcc, v2, v144
	v_add_u32_e32 v2, 49, v0
	s_nop 0
	v_cndmask_b32_e32 v88, v230, v88, vcc
	v_cmp_le_i32_e32 vcc, v2, v144
	v_add_u32_e32 v2, 50, v0
	s_nop 0
	v_cndmask_b32_e32 v89, v230, v89, vcc
	v_cmp_le_i32_e32 vcc, v2, v144
	v_add_u32_e32 v2, 51, v0
	s_nop 0
	v_cndmask_b32_e32 v90, v230, v90, vcc
	v_cmp_le_i32_e32 vcc, v2, v144
	v_add_u32_e32 v2, 56, v0
	s_nop 0
	v_cndmask_b32_e32 v91, v230, v91, vcc
	v_cmp_le_i32_e32 vcc, v2, v144
	v_add_u32_e32 v2, 57, v0
	s_nop 0
	v_cndmask_b32_e32 v92, v230, v92, vcc
	v_cmp_le_i32_e32 vcc, v2, v144
	v_add_u32_e32 v2, 58, v0
	v_add_u32_e32 v0, 59, v0
	v_cndmask_b32_e32 v93, v230, v93, vcc
	v_cmp_le_i32_e32 vcc, v2, v144
	s_nop 1
	v_cndmask_b32_e32 v94, v230, v94, vcc
	v_cmp_le_i32_e32 vcc, v0, v144
	s_nop 1
	v_cndmask_b32_e32 v95, v230, v95, vcc
.LBB0_240:
	s_nop 7
	s_nop 3
	v_max_f32_e32 v0, v96, v97
	v_max3_f32 v0, v0, v98, v99
	v_max3_f32 v0, v0, v100, v101
	v_max3_f32 v0, v0, v102, v103
	v_max3_f32 v0, v0, v104, v105
	v_max3_f32 v0, v0, v106, v107
	v_max3_f32 v0, v0, v108, v109
	v_max3_f32 v0, v0, v110, v111
	v_max3_f32 v0, v0, v80, v81
	v_max3_f32 v0, v0, v82, v83
	v_max3_f32 v0, v0, v84, v85
	v_max3_f32 v0, v0, v86, v87
	v_max3_f32 v0, v0, v88, v89
	v_max3_f32 v0, v0, v90, v91
	v_max3_f32 v0, v0, v92, v93
	v_max3_f32 v0, v0, v94, v95
	v_mov_b32_e32 v2, v0
	s_nop 1
	v_permlane32_swap_b32_e32 v0, v2
	v_max_f32_e32 v0, v0, v2
	s_cmp_eq_u32 s96, 0
	s_cselect_b64 s[0:1], -1, 0
	v_cmp_lt_f32_e32 vcc, s6, v0
	s_or_b64 vcc, s[0:1], vcc
	s_cbranch_vccz .LBB0_242
	v_max_f32_e32 v2, v0, v0
	v_max_f32_e32 v2, 0, v2
	v_cndmask_b32_e64 v0, v2, v0, s[0:1]
	v_exp_f32_e64 v2, -v0
	v_add_f32_e32 v161, v161, v0
	v_pk_add_f32 v[96:97], v[96:97], v[0:1] op_sel_hi:[1,0] neg_lo:[0,1] neg_hi:[0,1]
	v_pk_add_f32 v[98:99], v[98:99], v[0:1] op_sel_hi:[1,0] neg_lo:[0,1] neg_hi:[0,1]
	v_pk_mul_f32 v[78:79], v[78:79], v[2:3] op_sel_hi:[1,0]
	v_pk_mul_f32 v[76:77], v[76:77], v[2:3] op_sel_hi:[1,0]
	v_pk_mul_f32 v[74:75], v[74:75], v[2:3] op_sel_hi:[1,0]
	v_pk_mul_f32 v[72:73], v[72:73], v[2:3] op_sel_hi:[1,0]
	v_pk_mul_f32 v[70:71], v[70:71], v[2:3] op_sel_hi:[1,0]
	v_pk_mul_f32 v[68:69], v[68:69], v[2:3] op_sel_hi:[1,0]
	v_pk_mul_f32 v[66:67], v[66:67], v[2:3] op_sel_hi:[1,0]
	v_pk_mul_f32 v[64:65], v[64:65], v[2:3] op_sel_hi:[1,0]
	v_pk_mul_f32 v[62:63], v[62:63], v[2:3] op_sel_hi:[1,0]
	v_pk_mul_f32 v[60:61], v[60:61], v[2:3] op_sel_hi:[1,0]
	v_pk_mul_f32 v[58:59], v[58:59], v[2:3] op_sel_hi:[1,0]
	v_pk_mul_f32 v[56:57], v[56:57], v[2:3] op_sel_hi:[1,0]
	v_pk_mul_f32 v[54:55], v[54:55], v[2:3] op_sel_hi:[1,0]
	v_pk_mul_f32 v[52:53], v[52:53], v[2:3] op_sel_hi:[1,0]
	v_pk_mul_f32 v[50:51], v[50:51], v[2:3] op_sel_hi:[1,0]
	v_pk_mul_f32 v[48:49], v[48:49], v[2:3] op_sel_hi:[1,0]
	v_pk_mul_f32 v[46:47], v[46:47], v[2:3] op_sel_hi:[1,0]
	v_pk_mul_f32 v[44:45], v[44:45], v[2:3] op_sel_hi:[1,0]
	v_pk_mul_f32 v[42:43], v[42:43], v[2:3] op_sel_hi:[1,0]
	v_pk_mul_f32 v[40:41], v[40:41], v[2:3] op_sel_hi:[1,0]
; template <int DQK, int KROW, bool BIAS, bool MAPS2>
; DI void attn_core(const int t, const u16* __restrict__ Q, int ldq, const u16* __restrict__ Kp, int ldk, const u16* __restrict__ Vt, int q0,
;                   char* lds, const float* lut, float b31, f32x16 (&o)[4], float& l_out) {
;     ...
;       if (__builtin_amdgcn_ballot_w64(kt == 0 || mx > RESCALE_THR)) {
;         const float delta = (kt == 0) ? mx : fmaxf(mx, 0.f);
;         const float alpha = __builtin_amdgcn_exp2f(-delta);
;         m_run += delta;
;         l_run *= alpha;
; #pragma unroll
;         for (int dt = 0; dt < 4; ++dt)
; #pragma unroll
;           for (int i = 0; i < 16; ++i) o[dt][i] *= alpha;
; #pragma unroll
;         for (int k2 = 0; k2 < 2; ++k2)
; #pragma unroll
;           for (int i = 0; i < 16; ++i) s[k2][i] -= delta;
;       }
	v_pk_mul_f32 v[38:39], v[38:39], v[2:3] op_sel_hi:[1,0]
	v_pk_mul_f32 v[36:37], v[36:37], v[2:3] op_sel_hi:[1,0]
	v_pk_mul_f32 v[34:35], v[34:35], v[2:3] op_sel_hi:[1,0]
	v_pk_mul_f32 v[32:33], v[32:33], v[2:3] op_sel_hi:[1,0]
	v_pk_mul_f32 v[30:31], v[30:31], v[2:3] op_sel_hi:[1,0]
	v_pk_mul_f32 v[28:29], v[28:29], v[2:3] op_sel_hi:[1,0]
	v_pk_mul_f32 v[26:27], v[26:27], v[2:3] op_sel_hi:[1,0]
	v_pk_mul_f32 v[24:25], v[24:25], v[2:3] op_sel_hi:[1,0]
	v_pk_mul_f32 v[22:23], v[22:23], v[2:3] op_sel_hi:[1,0]
	v_pk_mul_f32 v[20:21], v[20:21], v[2:3] op_sel_hi:[1,0]
	v_pk_mul_f32 v[18:19], v[18:19], v[2:3] op_sel_hi:[1,0]
	v_pk_mul_f32 v[16:17], v[16:17], v[2:3] op_sel_hi:[1,0]
	v_pk_add_f32 v[100:101], v[100:101], v[0:1] op_sel_hi:[1,0] neg_lo:[0,1] neg_hi:[0,1]
	v_pk_add_f32 v[102:103], v[102:103], v[0:1] op_sel_hi:[1,0] neg_lo:[0,1] neg_hi:[0,1]
	v_pk_add_f32 v[104:105], v[104:105], v[0:1] op_sel_hi:[1,0] neg_lo:[0,1] neg_hi:[0,1]
	v_pk_add_f32 v[106:107], v[106:107], v[0:1] op_sel_hi:[1,0] neg_lo:[0,1] neg_hi:[0,1]
	v_pk_add_f32 v[108:109], v[108:109], v[0:1] op_sel_hi:[1,0] neg_lo:[0,1] neg_hi:[0,1]
	v_pk_add_f32 v[110:111], v[110:111], v[0:1] op_sel_hi:[1,0] neg_lo:[0,1] neg_hi:[0,1]
	v_pk_add_f32 v[80:81], v[80:81], v[0:1] op_sel_hi:[1,0] neg_lo:[0,1] neg_hi:[0,1]
	v_pk_add_f32 v[82:83], v[82:83], v[0:1] op_sel_hi:[1,0] neg_lo:[0,1] neg_hi:[0,1]
	v_pk_add_f32 v[84:85], v[84:85], v[0:1] op_sel_hi:[1,0] neg_lo:[0,1] neg_hi:[0,1]
	v_pk_add_f32 v[86:87], v[86:87], v[0:1] op_sel_hi:[1,0] neg_lo:[0,1] neg_hi:[0,1]
	v_pk_add_f32 v[88:89], v[88:89], v[0:1] op_sel_hi:[1,0] neg_lo:[0,1] neg_hi:[0,1]
	v_pk_add_f32 v[90:91], v[90:91], v[0:1] op_sel_hi:[1,0] neg_lo:[0,1] neg_hi:[0,1]
	v_pk_add_f32 v[92:93], v[92:93], v[0:1] op_sel_hi:[1,0] neg_lo:[0,1] neg_hi:[0,1]
	v_pk_add_f32 v[94:95], v[94:95], v[0:1] op_sel_hi:[1,0] neg_lo:[0,1] neg_hi:[0,1]
	v_mul_f32_e32 v151, v151, v2
	v_pk_add_f32 v[188:189], v[188:189], v[0:1] op_sel_hi:[1,0] neg_lo:[0,1] neg_hi:[0,1]
	v_pk_add_f32 v[190:191], v[190:191], v[0:1] op_sel_hi:[1,0] neg_lo:[0,1] neg_hi:[0,1]
	v_pk_add_f32 v[192:193], v[192:193], v[0:1] op_sel_hi:[1,0] neg_lo:[0,1] neg_hi:[0,1]
	v_pk_add_f32 v[194:195], v[194:195], v[0:1] op_sel_hi:[1,0] neg_lo:[0,1] neg_hi:[0,1]
	v_pk_add_f32 v[196:197], v[196:197], v[0:1] op_sel_hi:[1,0] neg_lo:[0,1] neg_hi:[0,1]
	v_pk_add_f32 v[198:199], v[198:199], v[0:1] op_sel_hi:[1,0] neg_lo:[0,1] neg_hi:[0,1]
	v_pk_add_f32 v[200:201], v[200:201], v[0:1] op_sel_hi:[1,0] neg_lo:[0,1] neg_hi:[0,1]
	v_pk_add_f32 v[202:203], v[202:203], v[0:1] op_sel_hi:[1,0] neg_lo:[0,1] neg_hi:[0,1]
	v_pk_mul_f32 v[184:185], v[184:185], v[2:3] op_sel_hi:[1,0]
; #define MFMA32(a, b, c) __builtin_amdgcn_mfma_f32_32x32x16_bf16((a), (b), (c), 0, 0, 0)
; template <int DQK, int KROW, bool BIAS, bool MAPS2>
; DI void attn_core(const int t, const u16* __restrict__ Q, int ldq, const u16* __restrict__ Kp, int ldk, const u16* __restrict__ Vt, int q0,
;                   char* lds, const float* lut, float b31, f32x16 (&o)[4], float& l_out) {
;     ...
;       float ps = 0.f;
; #pragma unroll
;       for (int k2 = 0; k2 < 2; ++k2)
; #pragma unroll
;         for (int i = 0; i < 16; ++i) { const float pv = __builtin_amdgcn_exp2f(s[k2][i]); s[k2][i] = pv; ps += pv; }
;       l_run += ps;
;       bf16x8 vfb[2][4];
;       const char* vbase = lds + AT_VOFF + (kt & 1) * AT_VBUF + r * VS + hf * 16;
; #pragma unroll
;       for (int dt = 0; dt < 4; ++dt) vfb[0][dt] = *(const bf16x8*)(vbase + 32 * dt * VS);
; #pragma unroll
;       for (int bb = 0; bb < 4; ++bb) {
;         const int k2 = bb >> 1, s2 = bb & 1;
;         if (bb + 1 < 4) {
; #pragma unroll
;           for (int dt = 0; dt < 4; ++dt) vfb[(bb + 1) & 1][dt] = *(const bf16x8*)(vbase + 32 * dt * VS + (bb + 1) * 32);
;         }
;         u32x4 pp;
;         pp[0] = pk_bf16(s[k2][8 * s2 + 0], s[k2][8 * s2 + 1]);
;         pp[1] = pk_bf16(s[k2][8 * s2 + 2], s[k2][8 * s2 + 3]);
;         pp[2] = pk_bf16(s[k2][8 * s2 + 4], s[k2][8 * s2 + 5]);
;         pp[3] = pk_bf16(s[k2][8 * s2 + 6], s[k2][8 * s2 + 7]);
;         const bf16x8 pf = __builtin_bit_cast(bf16x8, pp);
;         __builtin_amdgcn_sched_barrier(0);
;         __builtin_amdgcn_s_setprio(1);
; #pragma unroll
;         for (int dt = 0; dt < 4; ++dt) o[dt] = MFMA32(vfb[bb & 1][dt], pf, o[dt]);
;         __builtin_amdgcn_s_setprio(0);
;         __builtin_amdgcn_sched_barrier(0);
;       }
;     }
;     __syncthreads();
.LBB0_242:
	v_exp_f32_e32 v0, v96
	v_exp_f32_e32 v14, v97
	v_exp_f32_e32 v15, v98
	v_add_f32_e32 v151, v151, v0
	v_exp_f32_e32 v162, v99
	v_mov_b64_e32 v[186:187], v[14:15]
	v_exp_f32_e32 v163, v100
	v_exp_f32_e32 v164, v101
	v_exp_f32_e32 v165, v102
	v_pk_add_f32 v[186:187], v[186:187], v[162:163]
	v_exp_f32_e32 v103, v103
	v_pk_add_f32 v[186:187], v[186:187], v[164:165]
	v_exp_f32_e32 v104, v104
	v_add_f32_e32 v151, v151, v103
	v_exp_f32_e32 v105, v105
	v_exp_f32_e32 v106, v106
	v_exp_f32_e32 v107, v107
	v_pk_add_f32 v[186:187], v[186:187], v[104:105]
	v_exp_f32_e32 v108, v108
	v_pk_add_f32 v[186:187], v[186:187], v[106:107]
	v_exp_f32_e32 v109, v109
	v_exp_f32_e32 v110, v110
	v_exp_f32_e32 v111, v111
	v_pk_add_f32 v[186:187], v[186:187], v[108:109]
	v_exp_f32_e32 v166, v80
	v_pk_add_f32 v[186:187], v[186:187], v[110:111]
	v_exp_f32_e32 v167, v81
	v_exp_f32_e32 v168, v82
	v_exp_f32_e32 v169, v83
	v_pk_add_f32 v[186:187], v[186:187], v[166:167]
	v_exp_f32_e32 v170, v84
	v_pk_add_f32 v[186:187], v[186:187], v[168:169]
	v_exp_f32_e32 v171, v85
	v_exp_f32_e32 v172, v86
	v_exp_f32_e32 v173, v87
	v_pk_add_f32 v[186:187], v[186:187], v[170:171]
	v_exp_f32_e32 v174, v88
	v_pk_add_f32 v[186:187], v[186:187], v[172:173]
	v_exp_f32_e32 v175, v89
	v_exp_f32_e32 v176, v90
	v_exp_f32_e32 v177, v91
	v_pk_add_f32 v[186:187], v[186:187], v[174:175]
	v_exp_f32_e32 v178, v92
	v_pk_add_f32 v[186:187], v[186:187], v[176:177]
	v_exp_f32_e32 v179, v93
	v_exp_f32_e32 v180, v94
	v_exp_f32_e32 v181, v95
	v_pk_add_f32 v[186:187], v[186:187], v[178:179]
	s_nop 0
	v_pk_add_f32 v[186:187], v[186:187], v[180:181]
	v_pk_add_f32 v[184:185], v[184:185], v[186:187]
	s_mulk_i32 s91, 0x4800
	v_add_u32_e32 v183, s91, v158
	ds_read_b128 v[2:5], v183 offset:51200
	ds_read_b128 v[6:9], v183 offset:51232
	ds_read_b128 v[10:13], v183 offset:55808
	ds_read_b128 v[80:83], v183 offset:55840
	ds_read_b128 v[84:87], v183 offset:60416
	ds_read_b128 v[88:91], v183 offset:60448
	ds_read_b128 v[92:95], v183 offset:65024
	ds_read_b128 v[96:99], v183 offset:65056
	v_cvt_pk_bf16_f32 v100, v0, v14
	v_cvt_pk_bf16_f32 v101, v15, v162
	v_cvt_pk_bf16_f32 v102, v163, v164
	v_cvt_pk_bf16_f32 v103, v165, v103
	s_setprio 1
	s_waitcnt lgkmcnt(7)
	v_mfma_f32_32x32x16_bf16 v[64:79], v[2:5], v[100:103], v[64:79]
	s_waitcnt lgkmcnt(5)
	v_mfma_f32_32x32x16_bf16 v[48:63], v[10:13], v[100:103], v[48:63]
	s_waitcnt lgkmcnt(3)
	v_mfma_f32_32x32x16_bf16 v[32:47], v[84:87], v[100:103], v[32:47]
	s_waitcnt lgkmcnt(1)
	v_mfma_f32_32x32x16_bf16 v[16:31], v[92:95], v[100:103], v[16:31]
	s_setprio 0
	ds_read_b128 v[2:5], v183 offset:51264
	ds_read_b128 v[10:13], v183 offset:55872
	ds_read_b128 v[84:87], v183 offset:60480
	ds_read_b128 v[92:95], v183 offset:65088
	v_cvt_pk_bf16_f32 v100, v104, v105
	v_cvt_pk_bf16_f32 v101, v106, v107
	v_cvt_pk_bf16_f32 v102, v108, v109
	v_cvt_pk_bf16_f32 v103, v110, v111
	s_setprio 1
	s_nop 0
	v_mfma_f32_32x32x16_bf16 v[64:79], v[6:9], v[100:103], v[64:79]
	v_mfma_f32_32x32x16_bf16 v[48:63], v[80:83], v[100:103], v[48:63]
	v_mfma_f32_32x32x16_bf16 v[32:47], v[88:91], v[100:103], v[32:47]
	s_waitcnt lgkmcnt(4)
	v_mfma_f32_32x32x16_bf16 v[16:31], v[96:99], v[100:103], v[16:31]
	s_setprio 0
	ds_read_b128 v[6:9], v183 offset:51296
	ds_read_b128 v[80:83], v183 offset:55904
	ds_read_b128 v[88:91], v183 offset:60512
	ds_read_b128 v[96:99], v183 offset:65120
	v_cvt_pk_bf16_f32 v100, v166, v167
	v_cvt_pk_bf16_f32 v101, v168, v169
	v_cvt_pk_bf16_f32 v102, v170, v171
	v_cvt_pk_bf16_f32 v103, v172, v173
	s_setprio 1
	s_waitcnt lgkmcnt(7)
	v_mfma_f32_32x32x16_bf16 v[64:79], v[2:5], v[100:103], v[64:79]
	s_waitcnt lgkmcnt(6)
	v_mfma_f32_32x32x16_bf16 v[48:63], v[10:13], v[100:103], v[48:63]
	s_waitcnt lgkmcnt(5)
	v_mfma_f32_32x32x16_bf16 v[32:47], v[84:87], v[100:103], v[32:47]
	s_waitcnt lgkmcnt(4)
	v_mfma_f32_32x32x16_bf16 v[16:31], v[92:95], v[100:103], v[16:31]
	s_setprio 0
	v_cvt_pk_bf16_f32 v2, v174, v175
	v_cvt_pk_bf16_f32 v3, v176, v177
	v_cvt_pk_bf16_f32 v4, v178, v179
	v_cvt_pk_bf16_f32 v5, v180, v181
	s_setprio 1
	s_waitcnt lgkmcnt(3)
	v_mfma_f32_32x32x16_bf16 v[64:79], v[6:9], v[2:5], v[64:79]
	s_waitcnt lgkmcnt(2)
	v_mfma_f32_32x32x16_bf16 v[48:63], v[80:83], v[2:5], v[48:63]
	s_waitcnt lgkmcnt(1)
	v_mfma_f32_32x32x16_bf16 v[32:47], v[88:91], v[2:5], v[32:47]
	s_waitcnt lgkmcnt(0)
	v_mfma_f32_32x32x16_bf16 v[16:31], v[96:99], v[2:5], v[16:31]
	s_setprio 0
.LBB0_243:
	s_add_i32 s90, s90, 64
	s_sub_i32 s100, s100, 64
	s_cmp_eq_u32 s94, s95
	s_waitcnt lgkmcnt(0)
	s_barrier
	s_cbranch_scc1 .Ldt_exit
	s_mov_b32 s96, s95
	s_add_i32 s95, s96, 1
	s_cmp_ge_i32 s95, s94
	s_cbranch_scc0 .LBB0_233
	s_branch .LBB0_235
.Ldt_exit:
	v_add_f32_e32 v151, v151, v184
	v_add_f32_e32 v151, v151, v185
	s_branch .LBB0_247

; __global__ void __launch_bounds__(NTHREADS, 2) fwd_kernel(Params p) {
;   __shared__ __attribute__((aligned(16))) char lds[LDS_BYTES];
	.amdhsa_kernel _Z10fwd_kernel6Params
		.amdhsa_group_segment_fixed_size 148480
		.amdhsa_private_segment_fixed_size 0
		.amdhsa_kernarg_size 544
		.amdhsa_user_sgpr_count 2
		.amdhsa_user_sgpr_dispatch_ptr 0
		.amdhsa_user_sgpr_queue_ptr 0
		.amdhsa_user_sgpr_kernarg_segment_ptr 1
		.amdhsa_user_sgpr_dispatch_id 0
		.amdhsa_user_sgpr_kernarg_preload_length 0
		.amdhsa_user_sgpr_kernarg_preload_offset 0
		.amdhsa_user_sgpr_private_segment_size 0
		.amdhsa_uses_dynamic_stack 0
		.amdhsa_enable_private_segment 0
		.amdhsa_system_sgpr_workgroup_id_x 1
		.amdhsa_system_sgpr_workgroup_id_y 0
		.amdhsa_system_sgpr_workgroup_id_z 0
		.amdhsa_system_sgpr_workgroup_info 0
		.amdhsa_system_vgpr_workitem_id 2
		.amdhsa_next_free_vgpr 248
		.amdhsa_next_free_sgpr 102
		.amdhsa_accum_offset 248
		.amdhsa_reserve_vcc 1
		.amdhsa_float_round_mode_32 0
		.amdhsa_float_round_mode_16_64 0
		.amdhsa_float_denorm_mode_32 3
		.amdhsa_float_denorm_mode_16_64 3
		.amdhsa_dx10_clamp 1
		.amdhsa_ieee_mode 1
		.amdhsa_fp16_overflow 0
		.amdhsa_tg_split 0
		.amdhsa_exception_fp_ieee_invalid_op 0
		.amdhsa_exception_fp_denorm_src 0
		.amdhsa_exception_fp_ieee_div_zero 0
		.amdhsa_exception_fp_ieee_overflow 0
		.amdhsa_exception_fp_ieee_underflow 0
		.amdhsa_exception_fp_ieee_inexact 0
		.amdhsa_exception_int_div_zero 0
	.end_amdhsa_kernel

; __global__ void __launch_bounds__(NTHREADS, 2) fwd_kernel(Params p) {
;   __shared__ __attribute__((aligned(16))) char lds[LDS_BYTES];
.Lfunc_end0:
	.size	_Z10fwd_kernel6Params, .Lfunc_end0-_Z10fwd_kernel6Params
	.set _Z10fwd_kernel6Params.num_vgpr, 248
	.set _Z10fwd_kernel6Params.num_agpr, 0
	.set _Z10fwd_kernel6Params.numbered_sgpr, 102
	.set _Z10fwd_kernel6Params.num_named_barrier, 0
	.set _Z10fwd_kernel6Params.private_seg_size, 0
	.set _Z10fwd_kernel6Params.uses_vcc, 1
	.set _Z10fwd_kernel6Params.uses_flat_scratch, 0
	.set _Z10fwd_kernel6Params.has_dyn_sized_stack, 0
	.set _Z10fwd_kernel6Params.has_recursion, 0
	.set _Z10fwd_kernel6Params.has_indirect_call, 0

; __global__ void __launch_bounds__(NTHREADS, 2) fwd_kernel(Params p) {
;   __shared__ __attribute__((aligned(16))) char lds[LDS_BYTES];
amdhsa.kernels:
  - .agpr_count:     0
    .args:
      - .offset:         0
        .size:           288
        .value_kind:     by_value
      - .offset:         288
        .size:           4
        .value_kind:     hidden_block_count_x
      - .offset:         292
        .size:           4
        .value_kind:     hidden_block_count_y
      - .offset:         296
        .size:           4
        .value_kind:     hidden_block_count_z
      - .offset:         300
        .size:           2
        .value_kind:     hidden_group_size_x
      - .offset:         302
        .size:           2
        .value_kind:     hidden_group_size_y
      - .offset:         304
        .size:           2
        .value_kind:     hidden_group_size_z
      - .offset:         306
        .size:           2
        .value_kind:     hidden_remainder_x
      - .offset:         308
        .size:           2
        .value_kind:     hidden_remainder_y
      - .offset:         310
        .size:           2
        .value_kind:     hidden_remainder_z
      - .offset:         328
        .size:           8
        .value_kind:     hidden_global_offset_x
      - .offset:         336
        .size:           8
        .value_kind:     hidden_global_offset_y
      - .offset:         344
        .size:           8
        .value_kind:     hidden_global_offset_z
      - .offset:         352
        .size:           2
        .value_kind:     hidden_grid_dims
      - .offset:         376
        .size:           8
        .value_kind:     hidden_multigrid_sync_arg
    .group_segment_fixed_size: 148480
    .kernarg_segment_align: 8
    .kernarg_segment_size: 544
    .language:       OpenCL C
    .language_version:
      - 2
      - 0
    .max_flat_workgroup_size: 512
    .name:           _Z10fwd_kernel6Params
    .private_segment_fixed_size: 0
    .sgpr_count:     108
    .sgpr_spill_count: 42
    .symbol:         _Z10fwd_kernel6Params.kd
    .uniform_work_group_size: 1
    .uses_dynamic_stack: false
    .vgpr_count:     248
    .vgpr_spill_count: 0
    .wavefront_size: 64
